# attention stash layout [row][lane] inside the wave's region: each stash store/load moves 1 KB contiguous instead of 64 lanes x 16 B at 256 B stride
# speedup vs baseline: 1.0122x; 1.0059x over previous
.LBB0_356:
	v_readfirstlane_b32 s96, v158
	v_readfirstlane_b32 s97, v159
	v_and_b32_e32 v254, 63, v162
	v_lshlrev_b32_e32 v254, 4, v254
	s_add_u32 s98, s96, 0x3000
	s_addc_u32 s99, s97, 0
	s_add_u32 s96, s96, 0x1000
	s_addc_u32 s97, s97, 0
	v_mov_b32_e32 v218, v68
	v_mov_b32_e32 v216, v163
	v_ashrrev_i32_e32 v217, 31, v163
	v_lshl_add_u64 v[216:217], v[216:217], 2, s[38:39]
	global_load_dword v204, v[216:217], off
	global_load_dword v205, v[216:217], off offset:128
	global_load_dword v206, v[216:217], off offset:256
	global_load_dword v207, v[216:217], off offset:384
	global_load_dwordx4 v[106:109], v254, s[96:97] offset:-4096
	global_load_dwordx4 v[110:113], v254, s[96:97] offset:-3072
	global_load_dwordx4 v[114:117], v254, s[96:97] offset:-2048
	global_load_dwordx4 v[118:121], v254, s[96:97] offset:-1024
	global_load_dwordx4 v[122:125], v254, s[96:97] offset:0
	global_load_dwordx4 v[126:129], v254, s[96:97] offset:1024
	global_load_dwordx4 v[130:133], v254, s[96:97] offset:2048
	global_load_dwordx4 v[134:137], v254, s[96:97] offset:3072
	global_load_dwordx4 v[138:141], v254, s[98:99] offset:-4096
	global_load_dwordx4 v[142:145], v254, s[98:99] offset:-3072
	global_load_dwordx4 v[146:149], v254, s[98:99] offset:-2048
	global_load_dwordx4 v[150:153], v254, s[98:99] offset:-1024
	global_load_dwordx4 v[154:157], v254, s[98:99] offset:0
	global_load_dwordx4 v[176:179], v254, s[98:99] offset:1024
	global_load_dwordx4 v[180:183], v254, s[98:99] offset:2048
	global_load_dwordx4 v[184:187], v254, s[98:99] offset:3072
	ds_read_b128 v[66:69], v218
	ds_read_b128 v[70:73], v218 offset:32
	ds_read_b128 v[74:77], v218 offset:64
	ds_read_b128 v[78:81], v218 offset:96
	s_add_u32 s100, s92, s20
	s_addc_u32 s101, s93, s21
	s_add_u32 s100, s100, 0x2e400000
	s_addc_u32 s101, s101, 0
	v_xor_b32_e32 v208, 16, v174
	v_lshlrev_b32_e32 v208, 2, v208
	s_waitcnt lgkmcnt(0)
	v_rcp_f32_e32 v66, v66
	v_rcp_f32_e32 v67, v67
	v_rcp_f32_e32 v68, v68
	v_rcp_f32_e32 v69, v69
	v_rcp_f32_e32 v70, v70
	v_rcp_f32_e32 v71, v71
	v_rcp_f32_e32 v72, v72
	v_rcp_f32_e32 v73, v73
	v_rcp_f32_e32 v74, v74
	v_rcp_f32_e32 v75, v75
	v_rcp_f32_e32 v76, v76
	v_rcp_f32_e32 v77, v77
	v_rcp_f32_e32 v78, v78
	v_rcp_f32_e32 v79, v79
	v_rcp_f32_e32 v80, v80
	v_rcp_f32_e32 v81, v81
	v_mul_f32_e32 v66, v1, v66
	v_mul_f32_e32 v67, v1, v67
	v_mul_f32_e32 v68, v1, v68
	v_mul_f32_e32 v69, v1, v69
	v_mul_f32_e32 v70, v1, v70
	v_mul_f32_e32 v71, v1, v71
	v_mul_f32_e32 v72, v1, v72
	v_mul_f32_e32 v73, v1, v73
	v_mul_f32_e32 v74, v1, v74
	v_mul_f32_e32 v75, v1, v75
	v_mul_f32_e32 v76, v1, v76
	v_mul_f32_e32 v77, v1, v77
	v_mul_f32_e32 v78, v1, v78
	v_mul_f32_e32 v79, v1, v79
	v_mul_f32_e32 v80, v1, v80
	v_mul_f32_e32 v81, v1, v81
	s_waitcnt vmcnt(15)
	v_fma_f32 v106, -v50, v66, v106
	v_fma_f32 v107, -v34, v66, v107
	v_fma_f32 v108, -v18, v66, v108
	v_fma_f32 v109, -v2, v66, v109
	v_mul_f32_e32 v204, 0x3f4ccccd, v204
	v_mul_f32_e32 v205, 0x3f4ccccd, v205
	v_mul_f32_e32 v206, 0x3f4ccccd, v206
	v_mul_f32_e32 v207, 0x3f4ccccd, v207
	v_mul_f32_e32 v66, v106, v106
	v_fmac_f32_e32 v66, v107, v107
	v_fmac_f32_e32 v66, v108, v108
	v_fmac_f32_e32 v66, v109, v109
	s_waitcnt vmcnt(14)
	v_fma_f32 v110, -v51, v67, v110
	v_fma_f32 v111, -v35, v67, v111
	v_fma_f32 v112, -v19, v67, v112
	v_fma_f32 v113, -v3, v67, v113
	v_mul_f32_e32 v67, v110, v110
	v_fmac_f32_e32 v67, v111, v111
	v_fmac_f32_e32 v67, v112, v112
	v_fmac_f32_e32 v67, v113, v113
	s_waitcnt vmcnt(13)
	v_fma_f32 v114, -v52, v68, v114
	v_fma_f32 v115, -v36, v68, v115
	v_fma_f32 v116, -v20, v68, v116
	v_fma_f32 v117, -v4, v68, v117
	v_mul_f32_e32 v68, v114, v114
	v_fmac_f32_e32 v68, v115, v115
	v_fmac_f32_e32 v68, v116, v116
	v_fmac_f32_e32 v68, v117, v117
	s_waitcnt vmcnt(12)
	v_fma_f32 v118, -v53, v69, v118
	v_fma_f32 v119, -v37, v69, v119
	v_fma_f32 v120, -v21, v69, v120
	v_fma_f32 v121, -v5, v69, v121
	v_mul_f32_e32 v69, v118, v118
	v_fmac_f32_e32 v69, v119, v119
	v_fmac_f32_e32 v69, v120, v120
	v_fmac_f32_e32 v69, v121, v121
	s_waitcnt vmcnt(11)
	v_fma_f32 v122, -v54, v70, v122
	v_fma_f32 v123, -v38, v70, v123
	v_fma_f32 v124, -v22, v70, v124
	v_fma_f32 v125, -v6, v70, v125
	v_mul_f32_e32 v70, v122, v122
	v_fmac_f32_e32 v70, v123, v123
	v_fmac_f32_e32 v70, v124, v124
	v_fmac_f32_e32 v70, v125, v125
	s_waitcnt vmcnt(10)
	v_fma_f32 v126, -v55, v71, v126
	v_fma_f32 v127, -v39, v71, v127
	v_fma_f32 v128, -v23, v71, v128
	v_fma_f32 v129, -v7, v71, v129
	v_mul_f32_e32 v71, v126, v126
	v_fmac_f32_e32 v71, v127, v127
	v_fmac_f32_e32 v71, v128, v128
	v_fmac_f32_e32 v71, v129, v129
	s_waitcnt vmcnt(9)
	v_fma_f32 v130, -v56, v72, v130
	v_fma_f32 v131, -v40, v72, v131
	v_fma_f32 v132, -v24, v72, v132
	v_fma_f32 v133, -v8, v72, v133
	v_mul_f32_e32 v72, v130, v130
	v_fmac_f32_e32 v72, v131, v131
	v_fmac_f32_e32 v72, v132, v132
	v_fmac_f32_e32 v72, v133, v133
	s_waitcnt vmcnt(8)
	v_fma_f32 v134, -v57, v73, v134
	v_fma_f32 v135, -v41, v73, v135
	v_fma_f32 v136, -v25, v73, v136
	v_fma_f32 v137, -v9, v73, v137
	v_mul_f32_e32 v73, v134, v134
	v_fmac_f32_e32 v73, v135, v135
	v_fmac_f32_e32 v73, v136, v136
	v_fmac_f32_e32 v73, v137, v137
	s_waitcnt vmcnt(7)
	v_fma_f32 v138, -v58, v74, v138
	v_fma_f32 v139, -v42, v74, v139
	v_fma_f32 v140, -v26, v74, v140
	v_fma_f32 v141, -v10, v74, v141
	v_mul_f32_e32 v74, v138, v138
	v_fmac_f32_e32 v74, v139, v139
	v_fmac_f32_e32 v74, v140, v140
	v_fmac_f32_e32 v74, v141, v141
	s_waitcnt vmcnt(6)
	v_fma_f32 v142, -v59, v75, v142
	v_fma_f32 v143, -v43, v75, v143
	v_fma_f32 v144, -v27, v75, v144
	v_fma_f32 v145, -v11, v75, v145
	v_mul_f32_e32 v75, v142, v142
	v_fmac_f32_e32 v75, v143, v143
	v_fmac_f32_e32 v75, v144, v144
	v_fmac_f32_e32 v75, v145, v145
	s_waitcnt vmcnt(5)
	v_fma_f32 v146, -v60, v76, v146
	v_fma_f32 v147, -v44, v76, v147
	v_fma_f32 v148, -v28, v76, v148
	v_fma_f32 v149, -v12, v76, v149
	v_mul_f32_e32 v76, v146, v146
	v_fmac_f32_e32 v76, v147, v147
	v_fmac_f32_e32 v76, v148, v148
	v_fmac_f32_e32 v76, v149, v149
	s_waitcnt vmcnt(4)
	v_fma_f32 v150, -v61, v77, v150
	v_fma_f32 v151, -v45, v77, v151
	v_fma_f32 v152, -v29, v77, v152
	v_fma_f32 v153, -v13, v77, v153
	v_mul_f32_e32 v77, v150, v150
	v_fmac_f32_e32 v77, v151, v151
	v_fmac_f32_e32 v77, v152, v152
	v_fmac_f32_e32 v77, v153, v153
	s_waitcnt vmcnt(3)
	v_fma_f32 v154, -v62, v78, v154
	v_fma_f32 v155, -v46, v78, v155
	v_fma_f32 v156, -v30, v78, v156
	v_fma_f32 v157, -v14, v78, v157
	v_mul_f32_e32 v78, v154, v154
	v_fmac_f32_e32 v78, v155, v155
	v_fmac_f32_e32 v78, v156, v156
	v_fmac_f32_e32 v78, v157, v157
	s_waitcnt vmcnt(2)
	v_fma_f32 v176, -v63, v79, v176
	v_fma_f32 v177, -v47, v79, v177
	v_fma_f32 v178, -v31, v79, v178
	v_fma_f32 v179, -v15, v79, v179
	v_mul_f32_e32 v79, v176, v176
	v_fmac_f32_e32 v79, v177, v177
	v_fmac_f32_e32 v79, v178, v178
	v_fmac_f32_e32 v79, v179, v179
	s_waitcnt vmcnt(1)
	v_fma_f32 v180, -v64, v80, v180
	v_fma_f32 v181, -v48, v80, v181
	v_fma_f32 v182, -v32, v80, v182
	v_fma_f32 v183, -v16, v80, v183
	v_mul_f32_e32 v80, v180, v180
	v_fmac_f32_e32 v80, v181, v181
	v_fmac_f32_e32 v80, v182, v182
	v_fmac_f32_e32 v80, v183, v183
	s_waitcnt vmcnt(0)
	v_fma_f32 v184, -v65, v81, v184
	v_fma_f32 v185, -v49, v81, v185
	v_fma_f32 v186, -v33, v81, v186
	v_fma_f32 v187, -v17, v81, v187
	v_mul_f32_e32 v81, v184, v184
	v_fmac_f32_e32 v81, v185, v185
	v_fmac_f32_e32 v81, v186, v186
	v_fmac_f32_e32 v81, v187, v187
	v_add_f32_dpp v66, v66, v66 quad_perm:[1,0,3,2] row_mask:0xf bank_mask:0xf
	v_add_f32_dpp v67, v67, v67 quad_perm:[1,0,3,2] row_mask:0xf bank_mask:0xf
	v_add_f32_dpp v68, v68, v68 quad_perm:[1,0,3,2] row_mask:0xf bank_mask:0xf
	v_add_f32_dpp v69, v69, v69 quad_perm:[1,0,3,2] row_mask:0xf bank_mask:0xf
	v_add_f32_dpp v70, v70, v70 quad_perm:[1,0,3,2] row_mask:0xf bank_mask:0xf
	v_add_f32_dpp v71, v71, v71 quad_perm:[1,0,3,2] row_mask:0xf bank_mask:0xf
	v_add_f32_dpp v72, v72, v72 quad_perm:[1,0,3,2] row_mask:0xf bank_mask:0xf
	v_add_f32_dpp v73, v73, v73 quad_perm:[1,0,3,2] row_mask:0xf bank_mask:0xf
	v_add_f32_dpp v74, v74, v74 quad_perm:[1,0,3,2] row_mask:0xf bank_mask:0xf
	v_add_f32_dpp v75, v75, v75 quad_perm:[1,0,3,2] row_mask:0xf bank_mask:0xf
	v_add_f32_dpp v76, v76, v76 quad_perm:[1,0,3,2] row_mask:0xf bank_mask:0xf
	v_add_f32_dpp v77, v77, v77 quad_perm:[1,0,3,2] row_mask:0xf bank_mask:0xf
	v_add_f32_dpp v78, v78, v78 quad_perm:[1,0,3,2] row_mask:0xf bank_mask:0xf
	v_add_f32_dpp v79, v79, v79 quad_perm:[1,0,3,2] row_mask:0xf bank_mask:0xf
	v_add_f32_dpp v80, v80, v80 quad_perm:[1,0,3,2] row_mask:0xf bank_mask:0xf
	v_add_f32_dpp v81, v81, v81 quad_perm:[1,0,3,2] row_mask:0xf bank_mask:0xf
	v_add_f32_dpp v66, v66, v66 quad_perm:[2,3,0,1] row_mask:0xf bank_mask:0xf
	v_add_f32_dpp v67, v67, v67 quad_perm:[2,3,0,1] row_mask:0xf bank_mask:0xf
	v_add_f32_dpp v68, v68, v68 quad_perm:[2,3,0,1] row_mask:0xf bank_mask:0xf
	v_add_f32_dpp v69, v69, v69 quad_perm:[2,3,0,1] row_mask:0xf bank_mask:0xf
	v_add_f32_dpp v70, v70, v70 quad_perm:[2,3,0,1] row_mask:0xf bank_mask:0xf
	v_add_f32_dpp v71, v71, v71 quad_perm:[2,3,0,1] row_mask:0xf bank_mask:0xf
	v_add_f32_dpp v72, v72, v72 quad_perm:[2,3,0,1] row_mask:0xf bank_mask:0xf
	v_add_f32_dpp v73, v73, v73 quad_perm:[2,3,0,1] row_mask:0xf bank_mask:0xf
	v_add_f32_dpp v74, v74, v74 quad_perm:[2,3,0,1] row_mask:0xf bank_mask:0xf
	v_add_f32_dpp v75, v75, v75 quad_perm:[2,3,0,1] row_mask:0xf bank_mask:0xf
	v_add_f32_dpp v76, v76, v76 quad_perm:[2,3,0,1] row_mask:0xf bank_mask:0xf
	v_add_f32_dpp v77, v77, v77 quad_perm:[2,3,0,1] row_mask:0xf bank_mask:0xf
	v_add_f32_dpp v78, v78, v78 quad_perm:[2,3,0,1] row_mask:0xf bank_mask:0xf
	v_add_f32_dpp v79, v79, v79 quad_perm:[2,3,0,1] row_mask:0xf bank_mask:0xf
	v_add_f32_dpp v80, v80, v80 quad_perm:[2,3,0,1] row_mask:0xf bank_mask:0xf
	v_add_f32_dpp v81, v81, v81 quad_perm:[2,3,0,1] row_mask:0xf bank_mask:0xf
	v_add_f32_dpp v66, v66, v66 row_half_mirror row_mask:0xf bank_mask:0xf
	v_add_f32_dpp v67, v67, v67 row_half_mirror row_mask:0xf bank_mask:0xf
	v_add_f32_dpp v68, v68, v68 row_half_mirror row_mask:0xf bank_mask:0xf
	v_add_f32_dpp v69, v69, v69 row_half_mirror row_mask:0xf bank_mask:0xf
	v_add_f32_dpp v70, v70, v70 row_half_mirror row_mask:0xf bank_mask:0xf
	v_add_f32_dpp v71, v71, v71 row_half_mirror row_mask:0xf bank_mask:0xf
	v_add_f32_dpp v72, v72, v72 row_half_mirror row_mask:0xf bank_mask:0xf
	v_add_f32_dpp v73, v73, v73 row_half_mirror row_mask:0xf bank_mask:0xf
	v_add_f32_dpp v74, v74, v74 row_half_mirror row_mask:0xf bank_mask:0xf
	v_add_f32_dpp v75, v75, v75 row_half_mirror row_mask:0xf bank_mask:0xf
	v_add_f32_dpp v76, v76, v76 row_half_mirror row_mask:0xf bank_mask:0xf
	v_add_f32_dpp v77, v77, v77 row_half_mirror row_mask:0xf bank_mask:0xf
	v_add_f32_dpp v78, v78, v78 row_half_mirror row_mask:0xf bank_mask:0xf
	v_add_f32_dpp v79, v79, v79 row_half_mirror row_mask:0xf bank_mask:0xf
	v_add_f32_dpp v80, v80, v80 row_half_mirror row_mask:0xf bank_mask:0xf
	v_add_f32_dpp v81, v81, v81 row_half_mirror row_mask:0xf bank_mask:0xf
	v_add_f32_dpp v66, v66, v66 row_mirror row_mask:0xf bank_mask:0xf
	v_add_f32_dpp v67, v67, v67 row_mirror row_mask:0xf bank_mask:0xf
	v_add_f32_dpp v68, v68, v68 row_mirror row_mask:0xf bank_mask:0xf
	v_add_f32_dpp v69, v69, v69 row_mirror row_mask:0xf bank_mask:0xf
	v_add_f32_dpp v70, v70, v70 row_mirror row_mask:0xf bank_mask:0xf
	v_add_f32_dpp v71, v71, v71 row_mirror row_mask:0xf bank_mask:0xf
	v_add_f32_dpp v72, v72, v72 row_mirror row_mask:0xf bank_mask:0xf
	v_add_f32_dpp v73, v73, v73 row_mirror row_mask:0xf bank_mask:0xf
	v_add_f32_dpp v74, v74, v74 row_mirror row_mask:0xf bank_mask:0xf
	v_add_f32_dpp v75, v75, v75 row_mirror row_mask:0xf bank_mask:0xf
	v_add_f32_dpp v76, v76, v76 row_mirror row_mask:0xf bank_mask:0xf
	v_add_f32_dpp v77, v77, v77 row_mirror row_mask:0xf bank_mask:0xf
	v_add_f32_dpp v78, v78, v78 row_mirror row_mask:0xf bank_mask:0xf
	v_add_f32_dpp v79, v79, v79 row_mirror row_mask:0xf bank_mask:0xf
	v_add_f32_dpp v80, v80, v80 row_mirror row_mask:0xf bank_mask:0xf
	v_add_f32_dpp v81, v81, v81 row_mirror row_mask:0xf bank_mask:0xf
	ds_bpermute_b32 v188, v208, v66
	ds_bpermute_b32 v189, v208, v67
	ds_bpermute_b32 v190, v208, v68
	ds_bpermute_b32 v191, v208, v69
	ds_bpermute_b32 v192, v208, v70
	ds_bpermute_b32 v193, v208, v71
	ds_bpermute_b32 v194, v208, v72
	ds_bpermute_b32 v195, v208, v73
	ds_bpermute_b32 v196, v208, v74
	ds_bpermute_b32 v197, v208, v75
	ds_bpermute_b32 v198, v208, v76
	ds_bpermute_b32 v199, v208, v77
	ds_bpermute_b32 v200, v208, v78
	ds_bpermute_b32 v201, v208, v79
	ds_bpermute_b32 v202, v208, v80
	ds_bpermute_b32 v203, v208, v81
	s_waitcnt lgkmcnt(0)
	v_add_f32_e32 v66, v66, v188
	v_add_f32_e32 v67, v67, v189
	v_add_f32_e32 v68, v68, v190
	v_add_f32_e32 v69, v69, v191
	v_add_f32_e32 v70, v70, v192
	v_add_f32_e32 v71, v71, v193
	v_add_f32_e32 v72, v72, v194
	v_add_f32_e32 v73, v73, v195
	v_add_f32_e32 v74, v74, v196
	v_add_f32_e32 v75, v75, v197
	v_add_f32_e32 v76, v76, v198
	v_add_f32_e32 v77, v77, v199
	v_add_f32_e32 v78, v78, v200
	v_add_f32_e32 v79, v79, v201
	v_add_f32_e32 v80, v80, v202
	v_add_f32_e32 v81, v81, v203
	v_fmamk_f32 v66, v66, 0x3c000000, v172
	v_fmamk_f32 v67, v67, 0x3c000000, v172
	v_fmamk_f32 v68, v68, 0x3c000000, v172
	v_fmamk_f32 v69, v69, 0x3c000000, v172
	v_fmamk_f32 v70, v70, 0x3c000000, v172
	v_fmamk_f32 v71, v71, 0x3c000000, v172
	v_fmamk_f32 v72, v72, 0x3c000000, v172
	v_fmamk_f32 v73, v73, 0x3c000000, v172
	v_fmamk_f32 v74, v74, 0x3c000000, v172
	v_fmamk_f32 v75, v75, 0x3c000000, v172
	v_fmamk_f32 v76, v76, 0x3c000000, v172
	v_fmamk_f32 v77, v77, 0x3c000000, v172
	v_fmamk_f32 v78, v78, 0x3c000000, v172
	v_fmamk_f32 v79, v79, 0x3c000000, v172
	v_fmamk_f32 v80, v80, 0x3c000000, v172
	v_fmamk_f32 v81, v81, 0x3c000000, v172
	v_rsq_f32_e32 v66, v66
	v_rsq_f32_e32 v67, v67
	v_rsq_f32_e32 v68, v68
	v_rsq_f32_e32 v69, v69
	v_rsq_f32_e32 v70, v70
	v_rsq_f32_e32 v71, v71
	v_rsq_f32_e32 v72, v72
	v_rsq_f32_e32 v73, v73
	v_rsq_f32_e32 v74, v74
	v_rsq_f32_e32 v75, v75
	v_rsq_f32_e32 v76, v76
	v_rsq_f32_e32 v77, v77
	v_rsq_f32_e32 v78, v78
	v_rsq_f32_e32 v79, v79
	v_rsq_f32_e32 v80, v80
	v_rsq_f32_e32 v81, v81
	s_nop 0
	s_mov_b32 s96, 0xaaaaaaaa
	s_mov_b32 s97, 0xaaaaaaaa
	s_mov_b32 s98, 0xcccccccc
	s_mov_b32 s99, 0xcccccccc
	v_mov_b32_e32 v202, 0x5040100
	v_mov_b32_e32 v203, 0x3020706
	v_cndmask_b32_e64 v202, v202, v203, s[96:97]
	v_and_b32_e32 v209, 3, v163
	v_lshl_add_u32 v209, v164, 2, v209
	v_add_u32_e32 v209, v175, v209
	v_lshlrev_b32_e32 v209, 12, v209
	v_lshrrev_b32_e32 v210, 2, v163
	v_lshl_add_u32 v209, v210, 3, v209
	v_mul_f32_e32 v198, v106, v66
	v_mul_f32_e32 v199, v110, v67
	v_mul_f32_e32 v200, v114, v68
	v_mul_f32_e32 v201, v118, v69
	v_mul_f32_e32 v198, v204, v198
	v_mul_f32_e32 v199, v204, v199
	v_mul_f32_e32 v200, v204, v200
	v_mul_f32_e32 v201, v204, v201
	v_cvt_pk_bf16_f32 v188, v198, v199
	v_cvt_pk_bf16_f32 v189, v200, v201
	s_nop 0
	v_mov_b32_dpp v190, v188 quad_perm:[1,0,3,2] row_mask:0xf bank_mask:0xf
	v_mov_b32_dpp v191, v189 quad_perm:[1,0,3,2] row_mask:0xf bank_mask:0xf
	v_perm_b32 v192, v190, v188, v202
	v_perm_b32 v193, v191, v189, v202
	v_cndmask_b32_e64 v194, v193, v192, s[98:99]
	s_nop 1
	v_mov_b32_dpp v195, v194 quad_perm:[2,3,0,1] row_mask:0xf bank_mask:0xf
	v_cndmask_b32_e64 v196, v192, v195, s[98:99]
	v_cndmask_b32_e64 v197, v195, v193, s[98:99]
	global_store_dwordx2 v209, v[196:197], s[100:101] offset:2048
	v_mul_f32_e32 v198, v107, v66
	v_mul_f32_e32 v199, v111, v67
	v_mul_f32_e32 v200, v115, v68
	v_mul_f32_e32 v201, v119, v69
	v_mul_f32_e32 v198, v205, v198
	v_mul_f32_e32 v199, v205, v199
	v_mul_f32_e32 v200, v205, v200
	v_mul_f32_e32 v201, v205, v201
	v_cvt_pk_bf16_f32 v188, v198, v199
	v_cvt_pk_bf16_f32 v189, v200, v201
	s_nop 0
	v_mov_b32_dpp v190, v188 quad_perm:[1,0,3,2] row_mask:0xf bank_mask:0xf
	v_mov_b32_dpp v191, v189 quad_perm:[1,0,3,2] row_mask:0xf bank_mask:0xf
	v_perm_b32 v192, v190, v188, v202
	v_perm_b32 v193, v191, v189, v202
	v_cndmask_b32_e64 v194, v193, v192, s[98:99]
	s_nop 1
	v_mov_b32_dpp v195, v194 quad_perm:[2,3,0,1] row_mask:0xf bank_mask:0xf
	v_cndmask_b32_e64 v216, v192, v195, s[98:99]
	v_cndmask_b32_e64 v217, v195, v193, s[98:99]
	global_store_dwordx2 v209, v[216:217], s[100:101] offset:2112
	v_mul_f32_e32 v198, v108, v66
	v_mul_f32_e32 v199, v112, v67
	v_mul_f32_e32 v200, v116, v68
	v_mul_f32_e32 v201, v120, v69
	v_mul_f32_e32 v198, v206, v198
	v_mul_f32_e32 v199, v206, v199
	v_mul_f32_e32 v200, v206, v200
	v_mul_f32_e32 v201, v206, v201
	v_cvt_pk_bf16_f32 v188, v198, v199
	v_cvt_pk_bf16_f32 v189, v200, v201
	s_nop 0
	v_mov_b32_dpp v190, v188 quad_perm:[1,0,3,2] row_mask:0xf bank_mask:0xf
	v_mov_b32_dpp v191, v189 quad_perm:[1,0,3,2] row_mask:0xf bank_mask:0xf
	v_perm_b32 v192, v190, v188, v202
	v_perm_b32 v193, v191, v189, v202
	v_cndmask_b32_e64 v194, v193, v192, s[98:99]
	s_nop 1
	v_mov_b32_dpp v195, v194 quad_perm:[2,3,0,1] row_mask:0xf bank_mask:0xf
	v_cndmask_b32_e64 v196, v192, v195, s[98:99]
	v_cndmask_b32_e64 v197, v195, v193, s[98:99]
	global_store_dwordx2 v209, v[196:197], s[100:101] offset:2176
	v_mul_f32_e32 v198, v109, v66
	v_mul_f32_e32 v199, v113, v67
	v_mul_f32_e32 v200, v117, v68
	v_mul_f32_e32 v201, v121, v69
	v_mul_f32_e32 v198, v207, v198
	v_mul_f32_e32 v199, v207, v199
	v_mul_f32_e32 v200, v207, v200
	v_mul_f32_e32 v201, v207, v201
	v_cvt_pk_bf16_f32 v188, v198, v199
	v_cvt_pk_bf16_f32 v189, v200, v201
	s_nop 0
	v_mov_b32_dpp v190, v188 quad_perm:[1,0,3,2] row_mask:0xf bank_mask:0xf
	v_mov_b32_dpp v191, v189 quad_perm:[1,0,3,2] row_mask:0xf bank_mask:0xf
	v_perm_b32 v192, v190, v188, v202
	v_perm_b32 v193, v191, v189, v202
	v_cndmask_b32_e64 v194, v193, v192, s[98:99]
	s_nop 1
	v_mov_b32_dpp v195, v194 quad_perm:[2,3,0,1] row_mask:0xf bank_mask:0xf
	v_cndmask_b32_e64 v216, v192, v195, s[98:99]
	v_cndmask_b32_e64 v217, v195, v193, s[98:99]
	global_store_dwordx2 v209, v[216:217], s[100:101] offset:2240
	v_add_u32_e32 v210, 0x8000, v209
	v_mul_f32_e32 v198, v122, v70
	v_mul_f32_e32 v199, v126, v71
	v_mul_f32_e32 v200, v130, v72
	v_mul_f32_e32 v201, v134, v73
	v_mul_f32_e32 v198, v204, v198
	v_mul_f32_e32 v199, v204, v199
	v_mul_f32_e32 v200, v204, v200
	v_mul_f32_e32 v201, v204, v201
	v_cvt_pk_bf16_f32 v188, v198, v199
	v_cvt_pk_bf16_f32 v189, v200, v201
	s_nop 0
	v_mov_b32_dpp v190, v188 quad_perm:[1,0,3,2] row_mask:0xf bank_mask:0xf
	v_mov_b32_dpp v191, v189 quad_perm:[1,0,3,2] row_mask:0xf bank_mask:0xf
	v_perm_b32 v192, v190, v188, v202
	v_perm_b32 v193, v191, v189, v202
	v_cndmask_b32_e64 v194, v193, v192, s[98:99]
	s_nop 1
	v_mov_b32_dpp v195, v194 quad_perm:[2,3,0,1] row_mask:0xf bank_mask:0xf
	v_cndmask_b32_e64 v196, v192, v195, s[98:99]
	v_cndmask_b32_e64 v197, v195, v193, s[98:99]
	global_store_dwordx2 v210, v[196:197], s[100:101] offset:2048
	v_mul_f32_e32 v198, v123, v70
	v_mul_f32_e32 v199, v127, v71
	v_mul_f32_e32 v200, v131, v72
	v_mul_f32_e32 v201, v135, v73
	v_mul_f32_e32 v198, v205, v198
	v_mul_f32_e32 v199, v205, v199
	v_mul_f32_e32 v200, v205, v200
	v_mul_f32_e32 v201, v205, v201
	v_cvt_pk_bf16_f32 v188, v198, v199
	v_cvt_pk_bf16_f32 v189, v200, v201
	s_nop 0
	v_mov_b32_dpp v190, v188 quad_perm:[1,0,3,2] row_mask:0xf bank_mask:0xf
	v_mov_b32_dpp v191, v189 quad_perm:[1,0,3,2] row_mask:0xf bank_mask:0xf
	v_perm_b32 v192, v190, v188, v202
	v_perm_b32 v193, v191, v189, v202
	v_cndmask_b32_e64 v194, v193, v192, s[98:99]
	s_nop 1
	v_mov_b32_dpp v195, v194 quad_perm:[2,3,0,1] row_mask:0xf bank_mask:0xf
	v_cndmask_b32_e64 v216, v192, v195, s[98:99]
	v_cndmask_b32_e64 v217, v195, v193, s[98:99]
	global_store_dwordx2 v210, v[216:217], s[100:101] offset:2112
	v_mul_f32_e32 v198, v124, v70
	v_mul_f32_e32 v199, v128, v71
	v_mul_f32_e32 v200, v132, v72
	v_mul_f32_e32 v201, v136, v73
	v_mul_f32_e32 v198, v206, v198
	v_mul_f32_e32 v199, v206, v199
	v_mul_f32_e32 v200, v206, v200
	v_mul_f32_e32 v201, v206, v201
	v_cvt_pk_bf16_f32 v188, v198, v199
	v_cvt_pk_bf16_f32 v189, v200, v201
	s_nop 0
	v_mov_b32_dpp v190, v188 quad_perm:[1,0,3,2] row_mask:0xf bank_mask:0xf
	v_mov_b32_dpp v191, v189 quad_perm:[1,0,3,2] row_mask:0xf bank_mask:0xf
	v_perm_b32 v192, v190, v188, v202
	v_perm_b32 v193, v191, v189, v202
	v_cndmask_b32_e64 v194, v193, v192, s[98:99]
	s_nop 1
	v_mov_b32_dpp v195, v194 quad_perm:[2,3,0,1] row_mask:0xf bank_mask:0xf
	v_cndmask_b32_e64 v196, v192, v195, s[98:99]
	v_cndmask_b32_e64 v197, v195, v193, s[98:99]
	global_store_dwordx2 v210, v[196:197], s[100:101] offset:2176
	v_mul_f32_e32 v198, v125, v70
	v_mul_f32_e32 v199, v129, v71
	v_mul_f32_e32 v200, v133, v72
	v_mul_f32_e32 v201, v137, v73
	v_mul_f32_e32 v198, v207, v198
	v_mul_f32_e32 v199, v207, v199
	v_mul_f32_e32 v200, v207, v200
	v_mul_f32_e32 v201, v207, v201
	v_cvt_pk_bf16_f32 v188, v198, v199
	v_cvt_pk_bf16_f32 v189, v200, v201
	s_nop 0
	v_mov_b32_dpp v190, v188 quad_perm:[1,0,3,2] row_mask:0xf bank_mask:0xf
	v_mov_b32_dpp v191, v189 quad_perm:[1,0,3,2] row_mask:0xf bank_mask:0xf
	v_perm_b32 v192, v190, v188, v202
	v_perm_b32 v193, v191, v189, v202
	v_cndmask_b32_e64 v194, v193, v192, s[98:99]
	s_nop 1
	v_mov_b32_dpp v195, v194 quad_perm:[2,3,0,1] row_mask:0xf bank_mask:0xf
	v_cndmask_b32_e64 v216, v192, v195, s[98:99]
	v_cndmask_b32_e64 v217, v195, v193, s[98:99]
	global_store_dwordx2 v210, v[216:217], s[100:101] offset:2240
	v_add_u32_e32 v210, 0x10000, v209
	v_mul_f32_e32 v198, v138, v74
	v_mul_f32_e32 v199, v142, v75
	v_mul_f32_e32 v200, v146, v76
	v_mul_f32_e32 v201, v150, v77
	v_mul_f32_e32 v198, v204, v198
	v_mul_f32_e32 v199, v204, v199
	v_mul_f32_e32 v200, v204, v200
	v_mul_f32_e32 v201, v204, v201
	v_cvt_pk_bf16_f32 v188, v198, v199
	v_cvt_pk_bf16_f32 v189, v200, v201
	s_nop 0
	v_mov_b32_dpp v190, v188 quad_perm:[1,0,3,2] row_mask:0xf bank_mask:0xf
	v_mov_b32_dpp v191, v189 quad_perm:[1,0,3,2] row_mask:0xf bank_mask:0xf
	v_perm_b32 v192, v190, v188, v202
	v_perm_b32 v193, v191, v189, v202
	v_cndmask_b32_e64 v194, v193, v192, s[98:99]
	s_nop 1
	v_mov_b32_dpp v195, v194 quad_perm:[2,3,0,1] row_mask:0xf bank_mask:0xf
	v_cndmask_b32_e64 v196, v192, v195, s[98:99]
	v_cndmask_b32_e64 v197, v195, v193, s[98:99]
	global_store_dwordx2 v210, v[196:197], s[100:101] offset:2048
	v_mul_f32_e32 v198, v139, v74
	v_mul_f32_e32 v199, v143, v75
	v_mul_f32_e32 v200, v147, v76
	v_mul_f32_e32 v201, v151, v77
	v_mul_f32_e32 v198, v205, v198
	v_mul_f32_e32 v199, v205, v199
	v_mul_f32_e32 v200, v205, v200
	v_mul_f32_e32 v201, v205, v201
	v_cvt_pk_bf16_f32 v188, v198, v199
	v_cvt_pk_bf16_f32 v189, v200, v201
	s_nop 0
	v_mov_b32_dpp v190, v188 quad_perm:[1,0,3,2] row_mask:0xf bank_mask:0xf
	v_mov_b32_dpp v191, v189 quad_perm:[1,0,3,2] row_mask:0xf bank_mask:0xf
	v_perm_b32 v192, v190, v188, v202
	v_perm_b32 v193, v191, v189, v202
	v_cndmask_b32_e64 v194, v193, v192, s[98:99]
	s_nop 1
	v_mov_b32_dpp v195, v194 quad_perm:[2,3,0,1] row_mask:0xf bank_mask:0xf
	v_cndmask_b32_e64 v216, v192, v195, s[98:99]
	v_cndmask_b32_e64 v217, v195, v193, s[98:99]
	global_store_dwordx2 v210, v[216:217], s[100:101] offset:2112
	v_mul_f32_e32 v198, v140, v74
	v_mul_f32_e32 v199, v144, v75
	v_mul_f32_e32 v200, v148, v76
	v_mul_f32_e32 v201, v152, v77
	v_mul_f32_e32 v198, v206, v198
	v_mul_f32_e32 v199, v206, v199
	v_mul_f32_e32 v200, v206, v200
	v_mul_f32_e32 v201, v206, v201
	v_cvt_pk_bf16_f32 v188, v198, v199
	v_cvt_pk_bf16_f32 v189, v200, v201
	s_nop 0
	v_mov_b32_dpp v190, v188 quad_perm:[1,0,3,2] row_mask:0xf bank_mask:0xf
	v_mov_b32_dpp v191, v189 quad_perm:[1,0,3,2] row_mask:0xf bank_mask:0xf
	v_perm_b32 v192, v190, v188, v202
	v_perm_b32 v193, v191, v189, v202
	v_cndmask_b32_e64 v194, v193, v192, s[98:99]
	s_nop 1
	v_mov_b32_dpp v195, v194 quad_perm:[2,3,0,1] row_mask:0xf bank_mask:0xf
	v_cndmask_b32_e64 v196, v192, v195, s[98:99]
	v_cndmask_b32_e64 v197, v195, v193, s[98:99]
	global_store_dwordx2 v210, v[196:197], s[100:101] offset:2176
	v_mul_f32_e32 v198, v141, v74
	v_mul_f32_e32 v199, v145, v75
	v_mul_f32_e32 v200, v149, v76
	v_mul_f32_e32 v201, v153, v77
	v_mul_f32_e32 v198, v207, v198
	v_mul_f32_e32 v199, v207, v199
	v_mul_f32_e32 v200, v207, v200
	v_mul_f32_e32 v201, v207, v201
	v_cvt_pk_bf16_f32 v188, v198, v199
	v_cvt_pk_bf16_f32 v189, v200, v201
	s_nop 0
	v_mov_b32_dpp v190, v188 quad_perm:[1,0,3,2] row_mask:0xf bank_mask:0xf
	v_mov_b32_dpp v191, v189 quad_perm:[1,0,3,2] row_mask:0xf bank_mask:0xf
	v_perm_b32 v192, v190, v188, v202
	v_perm_b32 v193, v191, v189, v202
	v_cndmask_b32_e64 v194, v193, v192, s[98:99]
	s_nop 1
	v_mov_b32_dpp v195, v194 quad_perm:[2,3,0,1] row_mask:0xf bank_mask:0xf
	v_cndmask_b32_e64 v216, v192, v195, s[98:99]
	v_cndmask_b32_e64 v217, v195, v193, s[98:99]
	global_store_dwordx2 v210, v[216:217], s[100:101] offset:2240
	v_add_u32_e32 v210, 0x18000, v209
	v_mul_f32_e32 v198, v154, v78
	v_mul_f32_e32 v199, v176, v79
	v_mul_f32_e32 v200, v180, v80
	v_mul_f32_e32 v201, v184, v81
	v_mul_f32_e32 v198, v204, v198
	v_mul_f32_e32 v199, v204, v199
	v_mul_f32_e32 v200, v204, v200
	v_mul_f32_e32 v201, v204, v201
	v_cvt_pk_bf16_f32 v188, v198, v199
	v_cvt_pk_bf16_f32 v189, v200, v201
	s_nop 0
	v_mov_b32_dpp v190, v188 quad_perm:[1,0,3,2] row_mask:0xf bank_mask:0xf
	v_mov_b32_dpp v191, v189 quad_perm:[1,0,3,2] row_mask:0xf bank_mask:0xf
	v_perm_b32 v192, v190, v188, v202
	v_perm_b32 v193, v191, v189, v202
	v_cndmask_b32_e64 v194, v193, v192, s[98:99]
	s_nop 1
	v_mov_b32_dpp v195, v194 quad_perm:[2,3,0,1] row_mask:0xf bank_mask:0xf
	v_cndmask_b32_e64 v196, v192, v195, s[98:99]
	v_cndmask_b32_e64 v197, v195, v193, s[98:99]
	global_store_dwordx2 v210, v[196:197], s[100:101] offset:2048
	v_mul_f32_e32 v198, v155, v78
	v_mul_f32_e32 v199, v177, v79
	v_mul_f32_e32 v200, v181, v80
	v_mul_f32_e32 v201, v185, v81
	v_mul_f32_e32 v198, v205, v198
	v_mul_f32_e32 v199, v205, v199
	v_mul_f32_e32 v200, v205, v200
	v_mul_f32_e32 v201, v205, v201
	v_cvt_pk_bf16_f32 v188, v198, v199
	v_cvt_pk_bf16_f32 v189, v200, v201
	s_nop 0
	v_mov_b32_dpp v190, v188 quad_perm:[1,0,3,2] row_mask:0xf bank_mask:0xf
	v_mov_b32_dpp v191, v189 quad_perm:[1,0,3,2] row_mask:0xf bank_mask:0xf
	v_perm_b32 v192, v190, v188, v202
	v_perm_b32 v193, v191, v189, v202
	v_cndmask_b32_e64 v194, v193, v192, s[98:99]
	s_nop 1
	v_mov_b32_dpp v195, v194 quad_perm:[2,3,0,1] row_mask:0xf bank_mask:0xf
	v_cndmask_b32_e64 v216, v192, v195, s[98:99]
	v_cndmask_b32_e64 v217, v195, v193, s[98:99]
	global_store_dwordx2 v210, v[216:217], s[100:101] offset:2112
	v_mul_f32_e32 v198, v156, v78
	v_mul_f32_e32 v199, v178, v79
	v_mul_f32_e32 v200, v182, v80
	v_mul_f32_e32 v201, v186, v81
	v_mul_f32_e32 v198, v206, v198
	v_mul_f32_e32 v199, v206, v199
	v_mul_f32_e32 v200, v206, v200
	v_mul_f32_e32 v201, v206, v201
	v_cvt_pk_bf16_f32 v188, v198, v199
	v_cvt_pk_bf16_f32 v189, v200, v201
	s_nop 0
	v_mov_b32_dpp v190, v188 quad_perm:[1,0,3,2] row_mask:0xf bank_mask:0xf
	v_mov_b32_dpp v191, v189 quad_perm:[1,0,3,2] row_mask:0xf bank_mask:0xf
	v_perm_b32 v192, v190, v188, v202
	v_perm_b32 v193, v191, v189, v202
	v_cndmask_b32_e64 v194, v193, v192, s[98:99]
	s_nop 1
	v_mov_b32_dpp v195, v194 quad_perm:[2,3,0,1] row_mask:0xf bank_mask:0xf
	v_cndmask_b32_e64 v196, v192, v195, s[98:99]
	v_cndmask_b32_e64 v197, v195, v193, s[98:99]
	global_store_dwordx2 v210, v[196:197], s[100:101] offset:2176
	v_mul_f32_e32 v198, v157, v78
	v_mul_f32_e32 v199, v179, v79
	v_mul_f32_e32 v200, v183, v80
	v_mul_f32_e32 v201, v187, v81
	v_mul_f32_e32 v198, v207, v198
	v_mul_f32_e32 v199, v207, v199
	v_mul_f32_e32 v200, v207, v200
	v_mul_f32_e32 v201, v207, v201
	v_cvt_pk_bf16_f32 v188, v198, v199
	v_cvt_pk_bf16_f32 v189, v200, v201
	s_nop 0
	v_mov_b32_dpp v190, v188 quad_perm:[1,0,3,2] row_mask:0xf bank_mask:0xf
	v_mov_b32_dpp v191, v189 quad_perm:[1,0,3,2] row_mask:0xf bank_mask:0xf
	v_perm_b32 v192, v190, v188, v202
	v_perm_b32 v193, v191, v189, v202
	v_cndmask_b32_e64 v194, v193, v192, s[98:99]
	s_nop 1
	v_mov_b32_dpp v195, v194 quad_perm:[2,3,0,1] row_mask:0xf bank_mask:0xf
	v_cndmask_b32_e64 v216, v192, v195, s[98:99]
	v_cndmask_b32_e64 v217, v195, v193, s[98:99]
	global_store_dwordx2 v210, v[216:217], s[100:101] offset:2240
	s_cbranch_execnz .LBB0_335
.LBB0_357:
	v_readfirstlane_b32 s96, v158
	v_readfirstlane_b32 s97, v159
	v_and_b32_e32 v254, 63, v162
	v_lshlrev_b32_e32 v254, 4, v254
	s_add_u32 s98, s96, 0x3000
	s_addc_u32 s99, s97, 0
	s_add_u32 s96, s96, 0x1000
	s_addc_u32 s97, s97, 0
	ds_read_b128 v[70:73], v68
	ds_read_b128 v[74:77], v68 offset:32
	v_mov_b32_e32 v67, v34
	v_mov_b32_e32 v80, v18
	v_mov_b32_e32 v66, v50
	s_waitcnt lgkmcnt(1)
	v_rcp_f32_e32 v34, v70
	v_rcp_f32_e32 v18, v71
	v_mov_b32_e32 v81, v2
	v_mov_b32_e32 v2, v19
	v_pk_mul_f32 v[78:79], v[66:67], v[34:35] op_sel_hi:[1,0]
	v_pk_mul_f32 v[80:81], v[80:81], v[34:35] op_sel_hi:[1,0]
	global_store_dwordx4 v254, v[78:81], s[96:97] offset:-4096
	v_mov_b32_e32 v34, v51
	s_nop 0
	v_pk_mul_f32 v[80:81], v[2:3], v[18:19] op_sel_hi:[1,0]
	v_rcp_f32_e32 v2, v72
	v_pk_mul_f32 v[78:79], v[34:35], v[18:19] op_sel_hi:[1,0]
	v_mov_b32_e32 v18, v52
	v_mov_b32_e32 v19, v36
	v_pk_mul_f32 v[70:71], v[18:19], v[2:3] op_sel_hi:[1,0]
	v_mov_b32_e32 v18, v20
	v_rcp_f32_e32 v20, v73
	v_mov_b32_e32 v19, v4
	v_pk_mul_f32 v[72:73], v[18:19], v[2:3] op_sel_hi:[1,0]
	v_mov_b32_e32 v36, v53
	v_mov_b32_e32 v4, v21
	s_waitcnt lgkmcnt(0)
	v_rcp_f32_e32 v18, v74
	v_pk_mul_f32 v[2:3], v[36:37], v[20:21] op_sel_hi:[1,0]
	v_pk_mul_f32 v[4:5], v[4:5], v[20:21] op_sel_hi:[1,0]
	v_rcp_f32_e32 v20, v75
	global_store_dwordx4 v254, v[2:5], s[96:97] offset:-1024
	global_store_dwordx4 v254, v[78:81], s[96:97] offset:-3072
	global_store_dwordx4 v254, v[70:73], s[96:97] offset:-2048
	v_mov_b32_e32 v2, v54
	v_mov_b32_e32 v3, v38
	v_mov_b32_e32 v4, v22
	v_mov_b32_e32 v5, v6
	v_pk_mul_f32 v[2:3], v[2:3], v[18:19] op_sel_hi:[1,0]
	v_pk_mul_f32 v[4:5], v[4:5], v[18:19] op_sel_hi:[1,0]
	v_mov_b32_e32 v6, v23
	global_store_dwordx4 v254, v[2:5], s[96:97] offset:0
	v_mov_b32_e32 v38, v55
	v_rcp_f32_e32 v18, v77
	v_pk_mul_f32 v[4:5], v[6:7], v[20:21] op_sel_hi:[1,0]
	v_rcp_f32_e32 v6, v76
	v_pk_mul_f32 v[2:3], v[38:39], v[20:21] op_sel_hi:[1,0]
	global_store_dwordx4 v254, v[2:5], s[96:97] offset:1024
	s_nop 1
	v_mov_b32_e32 v2, v56
	v_mov_b32_e32 v3, v40
	v_mov_b32_e32 v4, v24
	v_mov_b32_e32 v5, v8
	v_pk_mul_f32 v[2:3], v[2:3], v[6:7] op_sel_hi:[1,0]
	v_pk_mul_f32 v[4:5], v[4:5], v[6:7] op_sel_hi:[1,0]
	global_store_dwordx4 v254, v[2:5], s[96:97] offset:2048
	ds_read_b128 v[2:5], v68 offset:64
	v_mov_b32_e32 v40, v57
	v_mov_b32_e32 v8, v25
	v_pk_mul_f32 v[6:7], v[40:41], v[18:19] op_sel_hi:[1,0]
	v_pk_mul_f32 v[8:9], v[8:9], v[18:19] op_sel_hi:[1,0]
	ds_read_b128 v[18:21], v68 offset:96
	s_waitcnt lgkmcnt(1)
	v_rcp_f32_e32 v2, v2
	v_rcp_f32_e32 v22, v3
	global_store_dwordx4 v254, v[6:9], s[96:97] offset:3072
	v_rcp_f32_e32 v4, v4
	s_nop 0
	v_mov_b32_e32 v6, v58
	v_mov_b32_e32 v7, v42
	v_mov_b32_e32 v8, v26
	v_mov_b32_e32 v9, v10
	v_pk_mul_f32 v[6:7], v[6:7], v[2:3] op_sel_hi:[1,0]
	v_pk_mul_f32 v[8:9], v[8:9], v[2:3] op_sel_hi:[1,0]
	v_mov_b32_e32 v42, v59
	v_mov_b32_e32 v10, v27
	global_store_dwordx4 v254, v[6:9], s[98:99] offset:-4096
	v_mov_b32_e32 v2, v60
	v_mov_b32_e32 v3, v44
	v_pk_mul_f32 v[6:7], v[42:43], v[22:23] op_sel_hi:[1,0]
	v_pk_mul_f32 v[8:9], v[10:11], v[22:23] op_sel_hi:[1,0]
	global_store_dwordx4 v254, v[6:9], s[98:99] offset:-3072
	v_pk_mul_f32 v[2:3], v[2:3], v[4:5] op_sel_hi:[1,0]
	v_mov_b32_e32 v44, v61
	v_rcp_f32_e32 v8, v5
	v_mov_b32_e32 v6, v28
	v_mov_b32_e32 v7, v12
	v_pk_mul_f32 v[4:5], v[6:7], v[4:5] op_sel_hi:[1,0]
	v_mov_b32_e32 v12, v29
	s_waitcnt lgkmcnt(0)
	v_rcp_f32_e32 v6, v18
	global_store_dwordx4 v254, v[2:5], s[98:99] offset:-2048
	s_nop 1
	v_pk_mul_f32 v[2:3], v[44:45], v[8:9] op_sel_hi:[1,0]
	v_pk_mul_f32 v[4:5], v[12:13], v[8:9] op_sel_hi:[1,0]
	v_rcp_f32_e32 v8, v19
	global_store_dwordx4 v254, v[2:5], s[98:99] offset:-1024
	s_nop 1
	v_mov_b32_e32 v2, v62
	v_mov_b32_e32 v3, v46
	v_mov_b32_e32 v4, v30
	v_mov_b32_e32 v5, v14
	v_pk_mul_f32 v[2:3], v[2:3], v[6:7] op_sel_hi:[1,0]
	v_pk_mul_f32 v[4:5], v[4:5], v[6:7] op_sel_hi:[1,0]
	v_mov_b32_e32 v46, v63
	v_mov_b32_e32 v14, v31
	v_rcp_f32_e32 v6, v20
	global_store_dwordx4 v254, v[2:5], s[98:99] offset:0
	s_nop 1
	v_pk_mul_f32 v[2:3], v[46:47], v[8:9] op_sel_hi:[1,0]
	v_pk_mul_f32 v[4:5], v[14:15], v[8:9] op_sel_hi:[1,0]
	v_rcp_f32_e32 v8, v21
	global_store_dwordx4 v254, v[2:5], s[98:99] offset:1024
	s_nop 1
	v_mov_b32_e32 v2, v64
	v_mov_b32_e32 v3, v48
	v_mov_b32_e32 v4, v32
	v_mov_b32_e32 v5, v16
	v_pk_mul_f32 v[2:3], v[2:3], v[6:7] op_sel_hi:[1,0]
	v_pk_mul_f32 v[4:5], v[4:5], v[6:7] op_sel_hi:[1,0]
	v_mov_b32_e32 v48, v65
	v_mov_b32_e32 v16, v33
	global_store_dwordx4 v254, v[2:5], s[98:99] offset:2048
	s_nop 1
	v_pk_mul_f32 v[2:3], v[48:49], v[8:9] op_sel_hi:[1,0]
	v_pk_mul_f32 v[4:5], v[16:17], v[8:9] op_sel_hi:[1,0]
	global_store_dwordx4 v254, v[2:5], s[98:99] offset:3072
	s_branch .LBB0_335
